# v21 plus: lru_conv sample-row path, the 24 conv-state loads issued together before the 24 state stores (was 8 serialised load-store round trips)
# baseline (speedup 1.0000x reference)
; #define INP(i) ((const float*)(const GASP float*)kargs()[(i)])
; #define OUTP ((float*)(GASP float*)kargs()[N_IN])
; __device__ __forceinline__ void unpack8(const u32x4 w, float (&x)[8]) { x[0] = bflo(w.x); x[1] = bfhi(w.x); x[2] = bflo(w.y); x[3] = bfhi(w.y); x[4] = bflo(w.z); x[5] = bfhi(w.z); x[6] = bflo(w.w); x[7] = bfhi(w.w); }
; __device__ __forceinline__ void lru_conv(const Frame& F, int j) {
;     ...
;         float x0[8], x1[8], x2[8], x3[8]; unpack8(raw[p][3], x3); unpack8(raw[p][2], x2); unpack8(raw[p][1], x1); unpack8(raw[p][0], x0);
;         if (row < TP) { const int t = row & 2047, b = row >> 11;
;             if (t >= 2045) { float* op = OUTP + O_PCONV + (size_t)((j * 4 + b) * 3 + (t - 2045)) * DRNN + c8; *(f32x4*)op = (f32x4){x3[0], x3[1], x3[2], x3[3]}; *(f32x4*)(op + 4) = (f32x4){x3[4], x3[5], x3[6], x3[7]}; }
;         } else { const int b = row - TP; const float* cbuf = INP(I_CONV) + (size_t)(j * 128 + b) * 3 * DRNN + c8; float* ob = OUTP + O_SCONV + (size_t)(j * 128 + b) * 3 * DRNN + c8;
; #pragma unroll
;             for (int e = 0; e < 8; ++e) { x0[e] = cbuf[e]; x1[e] = cbuf[DRNN + e]; x2[e] = cbuf[2 * DRNN + e]; ob[e] = x1[e]; ob[DRNN + e] = x2[e]; ob[2 * DRNN + e] = x3[e]; } }
.LBB0_663:
	s_or_b64 exec, exec, s[22:23]
	s_waitcnt vmcnt(1)
	v_lshlrev_b32_e32 v44, 16, v40
	v_and_b32_e32 v92, 0xffff0000, v40
	v_lshlrev_b32_e32 v46, 16, v41
	v_and_b32_e32 v90, 0xffff0000, v41
	v_lshlrev_b32_e32 v40, 16, v42
	v_and_b32_e32 v88, 0xffff0000, v42
	v_lshlrev_b32_e32 v42, 16, v43
	v_and_b32_e32 v86, 0xffff0000, v43
	s_and_saveexec_b64 s[16:17], vcc
	s_xor_b64 s[22:23], exec, s[16:17]
	s_cbranch_execz .LBB0_665
	s_mov_b64 s[16:17], s[0:1]
	s_load_dwordx2 s[16:17], s[16:17], 0x30
	v_readlane_b32 s15, v247, 58
	s_waitcnt lgkmcnt(0)
	v_mov_b64_e32 v[48:49], s[16:17]
	v_add_u32_e32 v41, s15, v110
	s_movk_i32 s15, 0x7800
	v_mad_u64_u32 v[48:49], s[16:17], v41, s15, v[48:49]
	v_lshl_add_u64 v[48:49], v[48:49], 0, v[62:63]
	v_add_co_u32_e32 v52, vcc, s89, v48
	s_mov_b64 s[16:17], s[0:1]
	s_nop 0
	v_addc_co_u32_e32 v53, vcc, 0, v49, vcc
	global_load_dword v94, v[48:49], off
	global_load_dword v95, v[52:53], off offset:2048
	v_add_co_u32_e32 v54, vcc, s13, v48
	s_load_dwordx2 s[16:17], s[16:17], 0x130
	s_nop 0
	v_addc_co_u32_e32 v55, vcc, 0, v49, vcc
	global_load_dword v45, v[54:55], off
	s_mov_b32 s13, 0xd010000
	s_waitcnt lgkmcnt(0)
	v_mov_b64_e32 v[50:51], s[16:17]
	v_mad_u64_u32 v[50:51], s[16:17], v41, s15, v[50:51]
	v_lshl_add_u64 v[56:57], v[50:51], 0, v[62:63]
	v_add_co_u32_e32 v58, vcc, s13, v56
	s_mov_b32 s13, 0xd012000
	s_nop 0
	v_addc_co_u32_e32 v59, vcc, 0, v57, vcc
	s_mov_b64 s[16:17], 0xd010000
	v_lshl_add_u64 v[50:51], v[56:57], 0, s[16:17]
	global_load_dword v96, v[48:49], off offset:4
	global_load_dword v97, v[52:53], off offset:2052
	global_load_dword v93, v[54:55], off offset:4
	global_load_dword v98, v[48:49], off offset:8
	global_load_dword v99, v[52:53], off offset:2056
	global_load_dword v47, v[54:55], off offset:8
	global_load_dword v100, v[48:49], off offset:12
	global_load_dword v101, v[52:53], off offset:2060
	global_load_dword v91, v[54:55], off offset:12
	global_load_dword v102, v[48:49], off offset:16
	global_load_dword v103, v[52:53], off offset:2064
	global_load_dword v41, v[54:55], off offset:16
	global_load_dword v104, v[48:49], off offset:20
	global_load_dword v105, v[52:53], off offset:2068
	global_load_dword v89, v[54:55], off offset:20
	global_load_dword v106, v[48:49], off offset:24
	global_load_dword v107, v[52:53], off offset:2072
	global_load_dword v43, v[54:55], off offset:24
	global_load_dword v108, v[48:49], off offset:28
	global_load_dword v109, v[52:53], off offset:2076
	global_load_dword v87, v[54:55], off offset:28
	s_waitcnt vmcnt(0)
	global_store_dword v[58:59], v95, off
	v_add_co_u32_e32 v58, vcc, s13, v56
	s_mov_b32 s13, 0xd015000
	s_nop 0
	v_addc_co_u32_e32 v59, vcc, 0, v57, vcc
	v_add_co_u32_e32 v56, vcc, s13, v56
	global_store_dword v[58:59], v45, off offset:2048
	v_addc_co_u32_e32 v57, vcc, 0, v57, vcc
	global_store_dword v[56:57], v44, off
	global_store_dword v[50:51], v97, off offset:4
	global_store_dword v[58:59], v93, off offset:2052
	global_store_dword v[56:57], v92, off offset:4
	global_store_dword v[50:51], v99, off offset:8
	global_store_dword v[58:59], v47, off offset:2056
	global_store_dword v[56:57], v46, off offset:8
	global_store_dword v[50:51], v101, off offset:12
	global_store_dword v[58:59], v91, off offset:2060
	global_store_dword v[56:57], v90, off offset:12
	global_store_dword v[50:51], v103, off offset:16
	global_store_dword v[58:59], v41, off offset:2064
	global_store_dword v[56:57], v40, off offset:16
	global_store_dword v[50:51], v105, off offset:20
	global_store_dword v[58:59], v89, off offset:2068
	global_store_dword v[56:57], v88, off offset:20
	global_store_dword v[50:51], v107, off offset:24
	global_store_dword v[58:59], v43, off offset:2072
	global_store_dword v[56:57], v42, off offset:24
	global_store_dword v[50:51], v109, off offset:28
	global_store_dword v[58:59], v87, off offset:2076
	global_store_dword v[56:57], v86, off offset:28

; __device__ __forceinline__ unsigned cvt_pk_bf16(float lo, float hi) { unsigned r; asm volatile("v_cvt_pk_bf16_f32 %0, %1, %2" : "=v"(r) : "v"(lo), "v"(hi)); return r; }
; #define INP(i) ((const float*)(const GASP float*)kargs()[(i)])
; #define OUTP ((float*)(GASP float*)kargs()[N_IN])
; __device__ __forceinline__ void unpack8(const u32x4 w, float (&x)[8]) { x[0] = bflo(w.x); x[1] = bfhi(w.x); x[2] = bflo(w.y); x[3] = bfhi(w.y); x[4] = bflo(w.z); x[5] = bfhi(w.z); x[6] = bflo(w.w); x[7] = bfhi(w.w); }
; __device__ __forceinline__ void lru_conv(const Frame& F, int j) {
;     ...
;         for (int p = 0; p < 2; ++p) { const int row = rowa + p * nrt; if (row < TT) {
;         float x0[8], x1[8], x2[8], x3[8]; unpack8(raw[p][3], x3); unpack8(raw[p][2], x2); unpack8(raw[p][1], x1); unpack8(raw[p][0], x0);
;         if (row < TP) { const int t = row & 2047, b = row >> 11;
;             if (t >= 2045) { float* op = OUTP + O_PCONV + (size_t)((j * 4 + b) * 3 + (t - 2045)) * DRNN + c8; *(f32x4*)op = (f32x4){x3[0], x3[1], x3[2], x3[3]}; *(f32x4*)(op + 4) = (f32x4){x3[4], x3[5], x3[6], x3[7]}; }
;         } else { const int b = row - TP; const float* cbuf = INP(I_CONV) + (size_t)(j * 128 + b) * 3 * DRNN + c8; float* ob = OUTP + O_SCONV + (size_t)(j * 128 + b) * 3 * DRNN + c8;
; #pragma unroll
;             for (int e = 0; e < 8; ++e) { x0[e] = cbuf[e]; x1[e] = cbuf[DRNN + e]; x2[e] = cbuf[2 * DRNN + e]; ob[e] = x1[e]; ob[DRNN + e] = x2[e]; ob[2 * DRNN + e] = x3[e]; } }
;         float xc[8];
; #pragma unroll
;         for (int e = 0; e < 8; ++e) xc[e] = bs[e] + x0[e] * w0[e] + x1[e] * w1[e] + x2[e] * w2[e] + x3[e] * w3[e];
;         u32x4 w; w.x = cvt_pk_bf16(xc[0], xc[1]); w.y = cvt_pk_bf16(xc[2], xc[3]); w.z = cvt_pk_bf16(xc[4], xc[5]); w.w = cvt_pk_bf16(xc[6], xc[7]); *(u32x4*)(XCB + (size_t)row * DRNN + c8) = w; } }
.LBB0_669:
	s_or_b64 exec, exec, s[22:23]
	v_pk_mul_f32 v[48:49], v[82:83], v[94:95]
	v_pk_mul_f32 v[44:45], v[80:81], v[44:45]
	v_add_f32_e32 v48, v0, v48
	v_add_f32_e32 v48, v48, v49
	v_add_f32_e32 v45, v45, v48
	v_add_f32_e32 v48, v44, v45
	v_pk_mul_f32 v[44:45], v[16:17], v[96:97]
	v_pk_mul_f32 v[40:41], v[72:73], v[40:41]
	v_add_f32_e32 v44, v1, v44
	v_add_f32_e32 v49, v44, v45
	v_pk_mul_f32 v[44:45], v[8:9], v[92:93]
	s_nop 0
	v_add_f32_e32 v45, v45, v49
	v_add_f32_e32 v49, v44, v45
	v_pk_mul_f32 v[44:45], v[78:79], v[98:99]
	s_nop 0
	v_add_f32_e32 v44, v2, v44
	v_add_f32_e32 v50, v44, v45
	v_pk_mul_f32 v[44:45], v[76:77], v[46:47]
	s_nop 0
	v_add_f32_e32 v45, v45, v50
	v_add_f32_e32 v46, v44, v45
	v_pk_mul_f32 v[44:45], v[18:19], v[100:101]
	s_nop 0
	v_add_f32_e32 v44, v3, v44
	v_add_f32_e32 v47, v44, v45
	v_pk_mul_f32 v[44:45], v[10:11], v[90:91]
	s_nop 0
	v_add_f32_e32 v45, v45, v47
	v_add_f32_e32 v47, v44, v45
	v_pk_mul_f32 v[44:45], v[74:75], v[102:103]
	s_nop 0
	v_add_f32_e32 v44, v4, v44
	v_add_f32_e32 v44, v44, v45
	v_add_f32_e32 v41, v41, v44
	v_add_f32_e32 v44, v40, v41
	v_pk_mul_f32 v[40:41], v[20:21], v[104:105]
	s_nop 0
	v_add_f32_e32 v40, v5, v40
	v_add_f32_e32 v45, v40, v41
	v_pk_mul_f32 v[40:41], v[12:13], v[88:89]
	s_nop 0
	v_add_f32_e32 v41, v41, v45
	v_add_f32_e32 v45, v40, v41
	v_pk_mul_f32 v[40:41], v[70:71], v[106:107]
	s_nop 0
	v_add_f32_e32 v40, v6, v40
	v_add_f32_e32 v50, v40, v41
	v_pk_mul_f32 v[40:41], v[68:69], v[42:43]
	s_nop 0
	v_add_f32_e32 v41, v41, v50
	v_add_f32_e32 v43, v40, v41
	v_pk_mul_f32 v[40:41], v[22:23], v[108:109]
	s_nop 0
	v_add_f32_e32 v40, v7, v40
	v_add_f32_e32 v42, v40, v41
	v_pk_mul_f32 v[40:41], v[14:15], v[86:87]
	s_nop 0
	v_add_f32_e32 v41, v41, v42
	v_add_f32_e32 v50, v40, v41
	v_cvt_pk_bf16_f32 v40, v48, v49
	v_cvt_pk_bf16_f32 v41, v46, v47
	v_cvt_pk_bf16_f32 v42, v44, v45
	v_lshl_add_u64 v[44:45], s[36:37], 0, v[84:85]
	v_cvt_pk_bf16_f32 v43, v43, v50
	global_store_dwordx4 v[44:45], v[40:43], off
	s_and_saveexec_b64 s[42:43], s[40:41]
	s_cbranch_execz .LBB0_650
	s_movk_i32 s13, 0x1fff
	s_waitcnt vmcnt(1)
	v_lshlrev_b32_e32 v40, 16, v36
	v_and_b32_e32 v50, 0xffff0000, v36
	v_lshlrev_b32_e32 v42, 16, v37
	v_and_b32_e32 v48, 0xffff0000, v37
	v_lshlrev_b32_e32 v36, 16, v38
	v_and_b32_e32 v46, 0xffff0000, v38
	v_lshlrev_b32_e32 v38, 16, v39
	v_and_b32_e32 v44, 0xffff0000, v39
	v_cmp_lt_i32_e32 vcc, s13, v111
	s_movk_i32 s13, 0x5000
	s_and_saveexec_b64 s[16:17], vcc
	s_xor_b64 s[22:23], exec, s[16:17]
	s_cbranch_execz .LBB0_672
	s_mov_b64 s[16:17], s[0:1]
	s_load_dwordx2 s[16:17], s[16:17], 0x30
	v_add_u32_e32 v28, s12, v110
	s_movk_i32 s15, 0x7800
	s_waitcnt lgkmcnt(0)
	v_mov_b64_e32 v[24:25], s[16:17]
	v_mad_u64_u32 v[24:25], s[16:17], v28, s15, v[24:25]
	s_mov_b64 s[16:17], s[0:1]
	s_load_dwordx2 s[16:17], s[16:17], 0x130
	v_lshl_add_u64 v[24:25], v[24:25], 0, v[62:63]
	global_load_dword v52, v[24:25], off
	s_waitcnt lgkmcnt(0)
	v_mov_b64_e32 v[26:27], s[16:17]
	v_mad_u64_u32 v[26:27], s[16:17], v28, s15, v[26:27]
	v_add_co_u32_e32 v28, vcc, s89, v24
	v_lshl_add_u64 v[32:33], v[26:27], 0, v[62:63]
	s_nop 0
	v_addc_co_u32_e32 v29, vcc, 0, v25, vcc
	global_load_dword v53, v[28:29], off offset:2048
	v_add_co_u32_e32 v30, vcc, s13, v24
	s_mov_b32 s13, 0xd010000
	s_nop 0
	v_addc_co_u32_e32 v31, vcc, 0, v25, vcc
	global_load_dword v41, v[30:31], off
	v_add_co_u32_e32 v34, vcc, s13, v32
	s_mov_b32 s13, 0xd012000
	s_nop 0
	v_addc_co_u32_e32 v35, vcc, 0, v33, vcc
	s_mov_b64 s[16:17], 0xd010000
	v_lshl_add_u64 v[26:27], v[32:33], 0, s[16:17]
	global_load_dword v54, v[24:25], off offset:4
	global_load_dword v55, v[28:29], off offset:2052
	global_load_dword v51, v[30:31], off offset:4
	global_load_dword v56, v[24:25], off offset:8
	global_load_dword v57, v[28:29], off offset:2056
	global_load_dword v43, v[30:31], off offset:8
	global_load_dword v58, v[24:25], off offset:12
	global_load_dword v59, v[28:29], off offset:2060
	global_load_dword v49, v[30:31], off offset:12
	global_load_dword v86, v[24:25], off offset:16
	global_load_dword v87, v[28:29], off offset:2064
	global_load_dword v37, v[30:31], off offset:16
	global_load_dword v88, v[24:25], off offset:20
	global_load_dword v89, v[28:29], off offset:2068
	global_load_dword v47, v[30:31], off offset:20
	global_load_dword v90, v[24:25], off offset:24
	global_load_dword v91, v[28:29], off offset:2072
	global_load_dword v39, v[30:31], off offset:24
	global_load_dword v92, v[24:25], off offset:28
	global_load_dword v93, v[28:29], off offset:2076
	global_load_dword v45, v[30:31], off offset:28
	s_waitcnt vmcnt(0)
	global_store_dword v[34:35], v53, off
	v_add_co_u32_e32 v34, vcc, s13, v32
	s_mov_b32 s13, 0xd015000
	s_nop 0
	v_addc_co_u32_e32 v35, vcc, 0, v33, vcc
	v_add_co_u32_e32 v32, vcc, s13, v32
	global_store_dword v[34:35], v41, off offset:2048
	v_addc_co_u32_e32 v33, vcc, 0, v33, vcc
	global_store_dword v[32:33], v40, off
	global_store_dword v[26:27], v55, off offset:4
	global_store_dword v[34:35], v51, off offset:2052
	global_store_dword v[32:33], v50, off offset:4
	global_store_dword v[26:27], v57, off offset:8
	global_store_dword v[34:35], v43, off offset:2056
	global_store_dword v[32:33], v42, off offset:8
	global_store_dword v[26:27], v59, off offset:12
	global_store_dword v[34:35], v49, off offset:2060
	global_store_dword v[32:33], v48, off offset:12
	global_store_dword v[26:27], v87, off offset:16
	global_store_dword v[34:35], v37, off offset:2064
	global_store_dword v[32:33], v36, off offset:16
	global_store_dword v[26:27], v89, off offset:20
	global_store_dword v[34:35], v47, off offset:2068
	global_store_dword v[32:33], v46, off offset:20
	global_store_dword v[26:27], v91, off offset:24
	global_store_dword v[34:35], v39, off offset:2072
	global_store_dword v[32:33], v38, off offset:24
	global_store_dword v[26:27], v93, off offset:28
	global_store_dword v[34:35], v45, off offset:2076
	global_store_dword v[32:33], v44, off offset:28
